# attention V tile: conflict-free LDS swizzle (staging source offset and fragment read offset)
# speedup vs baseline: 1.0097x; 1.0097x over previous
; __device__ __forceinline__ int opaque_tid(int wid_s) { int t = wid_s * 64 + lane_id_hw(); asm volatile("" : "+v"(t)); return t; }
; #define LAS __attribute__((address_space(3)))
; DI void attn_phase(const Params& p, const int layer, const int wid_s) {
;   const int tid = opaque_tid(wid_s), wave = __builtin_amdgcn_readfirstlane(tid >> 6), lane = tid & 63, fr = lane & 15, fq = lane >> 4;
;   const unsigned koff = (unsigned)(fr * LDH + fq * 8) * 2u, voff = (unsigned)(fr * 32 + fq * 8) * 2u;
;   LAS float* tab = (LAS float*)smem;
;   LAS float* impb = (LAS float*)((LAS unsigned char*)smem + 4224) + wave * 576 + fr * 36;
;   LAS float* impx = (LAS float*)((LAS unsigned char*)smem + 4224 + 18432) + lane;
;   LAS float* fin = (LAS float*)((LAS unsigned char*)smem + 4224 + 18432 + 16384) + wave * 2048 + lane;
;   {
;     const float* tg = (const float*)(p.ws + OFF_TAB);
;     for (int i = tid; i < 8 * 132; i += 512) tab[i] = tg[i];
;   }
;   __syncthreads();
;   if (tid < 8) { float bm = 0.f; for (int i = 0; i <= 128; ++i) bm = fmaxf(bm, tab[tid * 132 + i]); tab[tid * 132 + 129] = bm; tab[tid * 132 + 130] = MASKV; }
;   __syncthreads();
;     ...
;       { const int r = tid >> 3, cs = tid & 7, c = cs ^ (r & 7); k_src_off = r * LDH + c * 8; }
;       { const int i = tid & 255, r = i >> 2, cs = i & 3, c = cs ^ ((r >> 2) & 3); v_src_off = r * 32 + c * 8; }
;       const unsigned stage_dst = (unsigned)(wave < 4 ? wave * 1024 : 4096 + (wave - 4) * 1024);
;       unsigned kread[2][2], vread[4];
; #pragma unroll
;       for (int kt = 0; kt < 2; ++kt)
; #pragma unroll
;         for (int ks = 0; ks < 2; ++ks) { const int r = kt * 16 + fr, c = ks * 4 + fq; kread[kt][ks] = (unsigned)(r * 128 + ((c ^ (r & 7)) * 16)); }
; #pragma unroll
;       for (int dt = 0; dt < 4; ++dt) { const int r = dt * 16 + fr; vread[dt] = (unsigned)(4096 + r * 64 + ((fq ^ ((r >> 2) & 3)) * 16)); }
.LBB0_189:
	s_or_b64 exec, exec, s[0:1]
	v_mov_b32_e32 v198, v2
	v_min_u32_e32 v198, 0x293, v198
	v_sub_u32_e32 v199, 0x23f, v198
	v_cmp_gt_u32_e32 vcc, s33, v199
	v_min_u32_e32 v200, 0x80, v199
	v_lshlrev_b32_e32 v200, 2, v200
	v_lshlrev_b32_e32 v201, 2, v198
	v_add_u32_e32 v201, 0x22080, v201
	ds_read_b32 v202, v200 offset:0
	ds_read_b32 v203, v200 offset:528
	ds_read_b32 v204, v200 offset:1056
	ds_read_b32 v205, v200 offset:1584
	ds_read_b32 v206, v200 offset:2112
	ds_read_b32 v207, v200 offset:2640
	ds_read_b32 v208, v200 offset:3168
	ds_read_b32 v209, v200 offset:3696
	s_waitcnt lgkmcnt(0)
	v_cndmask_b32_e32 v202, v4, v202, vcc
	v_cndmask_b32_e32 v203, v4, v203, vcc
	v_cndmask_b32_e32 v204, v4, v204, vcc
	v_cndmask_b32_e32 v205, v4, v205, vcc
	v_cndmask_b32_e32 v206, v4, v206, vcc
	v_cndmask_b32_e32 v207, v4, v207, vcc
	v_cndmask_b32_e32 v208, v4, v208, vcc
	v_cndmask_b32_e32 v209, v4, v209, vcc
	ds_write_b32 v201, v202 offset:0
	ds_write_b32 v201, v203 offset:2640
	ds_write_b32 v201, v204 offset:5280
	ds_write_b32 v201, v205 offset:7920
	ds_write_b32 v201, v206 offset:10560
	ds_write_b32 v201, v207 offset:13200
	ds_write_b32 v201, v208 offset:15840
	ds_write_b32 v201, v209 offset:18480
	v_add_u32_e32 v198, 512, v2
	v_min_u32_e32 v198, 0x293, v198
	v_sub_u32_e32 v199, 0x23f, v198
	v_cmp_gt_u32_e32 vcc, s33, v199
	v_min_u32_e32 v200, 0x80, v199
	v_lshlrev_b32_e32 v200, 2, v200
	v_lshlrev_b32_e32 v201, 2, v198
	v_add_u32_e32 v201, 0x22080, v201
	ds_read_b32 v202, v200 offset:0
	ds_read_b32 v203, v200 offset:528
	ds_read_b32 v204, v200 offset:1056
	ds_read_b32 v205, v200 offset:1584
	ds_read_b32 v206, v200 offset:2112
	ds_read_b32 v207, v200 offset:2640
	ds_read_b32 v208, v200 offset:3168
	ds_read_b32 v209, v200 offset:3696
	s_waitcnt lgkmcnt(0)
	v_cndmask_b32_e32 v202, v4, v202, vcc
	v_cndmask_b32_e32 v203, v4, v203, vcc
	v_cndmask_b32_e32 v204, v4, v204, vcc
	v_cndmask_b32_e32 v205, v4, v205, vcc
	v_cndmask_b32_e32 v206, v4, v206, vcc
	v_cndmask_b32_e32 v207, v4, v207, vcc
	v_cndmask_b32_e32 v208, v4, v208, vcc
	v_cndmask_b32_e32 v209, v4, v209, vcc
	ds_write_b32 v201, v202 offset:0
	ds_write_b32 v201, v203 offset:2640
	ds_write_b32 v201, v204 offset:5280
	ds_write_b32 v201, v205 offset:7920
	ds_write_b32 v201, v206 offset:10560
	ds_write_b32 v201, v207 offset:13200
	ds_write_b32 v201, v208 offset:15840
	ds_write_b32 v201, v209 offset:18480
	s_ashr_i32 s0, s6, 6
	s_mul_i32 s1, s0, 0x900
	s_add_i32 s1, s1, 0
	v_and_b32_e32 v3, 63, v2
	v_and_b32_e32 v139, 15, v2
	v_mov_b32_e32 v0, s1
	s_mul_i32 s4, s0, 0x1700
	v_mad_u32_u24 v147, v139, s7, v0
	v_lshlrev_b32_e32 v0, 2, v3
	s_add_i32 s1, s1, s4
	v_readlane_b32 s4, v249, 10
	v_add_u32_e32 v177, 0, v0
	v_add_u32_e32 v178, s1, v0
	v_xor_b32_e32 v179, 64, v0
	v_xor_b32_e32 v180, 0x80, v0
	v_and_b32_e32 v0, 48, v2
	v_readlane_b32 s5, v249, 11
	s_lshl_b32 s1, s0, 4
	s_and_b32 s60, s1, 48
	v_lshl_add_u64 v[142:143], s[4:5], 0, v[0:1]
	v_lshl_add_u32 v0, v2, 2, v157
	s_ashr_i32 s1, s6, 7
	v_and_b32_e32 v181, 0xfc, v0
	v_ashrrev_i32_e32 v0, 3, v2
	s_and_b32 s61, s1, -2
	v_cmp_gt_u32_e64 s[62:63], 16, v3
	v_xor_b32_e32 v3, v0, v2
	s_movk_i32 s1, 0xa00
	v_mul_lo_u32 v0, v0, s1
	v_lshlrev_b32_e32 v3, 3, v3
	s_lshl_b32 s64, s0, 11
	v_and_or_b32 v144, v3, 56, v0
	v_lshrrev_b32_e32 v0, 4, v2
	v_xor_b32_e32 v0, v0, v2
	v_lshlrev_b32_e32 v3, 3, v2
	s_cmp_gt_i32 s0, 3
	v_bfe_u32 v141, v2, 4, 2
	v_and_b32_e32 v3, 0x7e0, v3
	v_lshlrev_b32_e32 v0, 3, v0
	s_cselect_b64 s[30:31], -1, 0
	s_lshl_b32 s22, s0, 10
	s_xor_b32 s0, s64, 0x2000
	v_writelane_b32 v249, s60, 53
	v_and_or_b32 v146, v0, 24, v3
	v_lshlrev_b32_e32 v3, 7, v139
	v_and_b32_e32 v5, 7, v2
	v_lshrrev_b32_e32 v0, 2, v2
	v_add_u32_e32 v182, s0, v177
	v_bitop3_b32 v2, v141, v2, 7 bitop3:0x78
	s_sub_i32 s0, s60, 19
	v_writelane_b32 v249, s61, 54
	v_lshlrev_b32_e32 v140, 6, v139
	v_bitop3_b32 v6, v141, v0, 3 bitop3:0x78
	v_and_b32_e32 v7, 12, v0
	v_lshlrev_b32_e32 v0, 2, v141
	v_bitop3_b32 v5, v141, v5, 4 bitop3:0x36
	v_lshl_or_b32 v185, v2, 4, v3
	v_add_u32_e32 v2, s0, v139
	v_writelane_b32 v249, s62, 55
	v_lshlrev_b32_e32 v138, 3, v141
	v_ashrrev_i32_e32 v145, 31, v144
	v_lshlrev_b32_e32 v148, 5, v139
	v_lshl_or_b32 v183, v6, 4, v140
	s_add_i32 s24, s22, 0x1d880
	v_lshl_or_b32 v184, v5, 4, v3
	v_sub_u32_e32 v186, v2, v7
	s_mov_b32 s0, 0
	v_lshlrev_b32_e32 v150, 1, v0
	s_mov_b32 s23, 0
	v_writelane_b32 v249, s63, 56
	v_mbcnt_lo_u32_b32 v198, -1, 0
	v_mbcnt_hi_u32_b32 v198, -1, v198
	v_mov_b32_e32 v199, 0x9c
	v_bfe_u32 v200, v198, 2, 2
	v_lshlrev_b32_e32 v200, 1, v200
	v_lshrrev_b32_e32 v200, v200, v199
	v_and_b32_e32 v200, 3, v200
	v_lshlrev_b32_e32 v200, 4, v200
	v_xor_b32_e32 v183, v183, v200
	v_bfe_u32 v200, v198, 4, 2
	v_lshlrev_b32_e32 v200, 1, v200
	v_lshrrev_b32_e32 v200, v200, v199
	v_and_b32_e32 v200, 3, v200
	v_lshlrev_b32_e32 v200, 3, v200
	v_xor_b32_e32 v146, v146, v200
	s_waitcnt lgkmcnt(0)
	s_barrier
	v_writelane_b32 v249, s64, 57
	s_branch .LBB0_192
